# P0: rope table computed by waves 4-7 of workgroups 0-3 (off the adaLN-gemv waves critical path); on top of static attention priority + hand-written P1/P6 + P4 epilogue hoist
# baseline (speedup 1.0000x reference)
; __global__ void __launch_bounds__(NWAVES * 64, 2) mk_fwd(Args args) {
;     ...
;         if (gtid < 1024) { const int pos = gtid >> 4, i = gtid & 15; const float fr = powf(10000.f, -(float)i / 16.f); const float ang = (float)pos * fr; float sn, cs; sincosf(ang, &sn, &cs); tab[gtid] = (f32x2){cs, sn}; }
.LBB0_127:
	s_or_b64 exec, exec, s[0:1]
	s_cmpk_lg_i32 s63, 0x100
	s_cbranch_scc1 .Lp0tab_keep
	v_lshl_add_u32 v4, s2, 8, v76
	v_subrev_u32_e32 v4, 0x100, v4
	v_mov_b32_e32 v5, 0x7fffffff
	v_cmp_gt_u32_e32 vcc, 0x100, v76
	s_nop 1
	v_cndmask_b32_e32 v4, v4, v5, vcc
.Lp0tab_keep:
	s_movk_i32 s0, 0x400
	v_cmp_gt_i32_e32 vcc, s0, v4
	s_and_saveexec_b64 s[8:9], vcc
	s_cbranch_execz .LBB0_133
	v_and_b32_e32 v0, 15, v76
	v_cvt_f32_ubyte0_e32 v0, v0
	v_mul_f32_e32 v16, 0xbd800000, v0
	v_mov_b32_e32 v0, 0x461c4000
	v_cmp_eq_f32_e32 vcc, 0, v16
	s_mov_b32 s0, 0x3f2aaaab
	s_movk_i32 s4, 0x204
	v_cndmask_b32_e64 v12, v0, 1.0, vcc
	v_frexp_mant_f32_e32 v0, v12
	v_cmp_gt_f32_e64 s[0:1], s0, v0
	s_mov_b32 s6, 0x42b17218
	s_mov_b32 s5, 0x7f800000
	v_cndmask_b32_e64 v1, 1.0, 2.0, s[0:1]
	v_mul_f32_e32 v0, v0, v1
	v_add_f32_e32 v3, 1.0, v0
	v_rcp_f32_e32 v10, v3
	v_add_f32_e32 v1, -1.0, v3
	v_sub_f32_e32 v7, v0, v1
	v_add_f32_e32 v1, -1.0, v0
	v_mul_f32_e32 v11, v1, v10
	v_mul_f32_e32 v2, v3, v11
	v_fma_f32 v6, v11, v3, -v2
	v_fmac_f32_e32 v6, v11, v7
	v_add_f32_e32 v0, v2, v6
	v_sub_f32_e32 v3, v1, v0
	v_pk_add_f32 v[8:9], v[0:1], v[2:3] neg_lo:[0,1] neg_hi:[0,1]
	v_mov_b32_e32 v7, v0
	v_pk_add_f32 v[0:1], v[8:9], v[6:7] neg_lo:[0,1] neg_hi:[0,1]
	v_mov_b32_e32 v6, 0x3e91f4c4
	v_add_f32_e32 v0, v0, v1
	v_add_f32_e32 v0, v3, v0
	v_mul_f32_e32 v1, v10, v0
	v_add_f32_e32 v0, v11, v1
	v_sub_f32_e32 v2, v0, v11
	v_sub_f32_e32 v13, v1, v2
	v_mul_f32_e32 v1, v0, v0
	v_fma_f32 v3, v0, v0, -v1
	v_add_f32_e32 v2, v13, v13
	v_fmac_f32_e32 v3, v0, v2
	v_add_f32_e32 v2, v1, v3
	v_fmac_f32_e32 v6, 0x3e76c4e1, v2
	v_fmaak_f32 v6, v2, v6, 0x3ecccdef
	v_sub_f32_e32 v1, v2, v1
	v_sub_f32_e32 v14, v3, v1
	v_mul_f32_e32 v1, v2, v6
	v_fma_f32 v3, v2, v6, -v1
	v_fmac_f32_e32 v3, v14, v6
	v_add_f32_e32 v6, v1, v3
	v_add_f32_e32 v7, 0x3f2aaaaa, v6
	v_sub_f32_e32 v1, v6, v1
	v_sub_f32_e32 v1, v3, v1
	v_add_f32_e32 v3, 0xbf2aaaaa, v7
	v_add_f32_e32 v1, 0x31739010, v1
	v_sub_f32_e32 v3, v6, v3
	v_pk_mul_f32 v[8:9], v[0:1], v[2:3]
	v_pk_add_f32 v[10:11], v[0:1], v[2:3]
	v_fma_f32 v6, v2, v0, -v8
	v_fmac_f32_e32 v6, v2, v13
	v_mov_b32_e32 v9, v11
	v_fmac_f32_e32 v6, v14, v0
	v_pk_add_f32 v[2:3], v[8:9], v[6:7]
	v_ldexp_f32 v14, v13, 1
	v_sub_f32_e32 v1, v2, v8
	v_sub_f32_e32 v1, v6, v1
	v_sub_f32_e32 v6, v7, v3
	v_add_f32_e32 v9, v11, v6
	v_pk_mul_f32 v[6:7], v[2:3], v[2:3] op_sel:[0,1] op_sel_hi:[1,0]
	v_cvt_f64_f32_e32 v[10:11], v12
	v_frexp_exp_i32_f64_e32 v7, v[10:11]
	v_subbrev_co_u32_e64 v7, s[0:1], 0, v7, s[0:1]
	v_cvt_f32_i32_e32 v7, v7
	v_fma_f32 v8, v2, v3, -v6
	v_fmac_f32_e32 v8, v2, v9
	s_mov_b32 s0, 0x3f317218
	v_mul_f32_e32 v2, 0x3f317218, v7
	v_fmac_f32_e32 v8, v1, v3
	v_fma_f32 v1, v7, s0, -v2
	v_fmamk_f32 v10, v7, 0xb102e308, v1
	v_ldexp_f32 v11, v0, 1
	v_add_f32_e32 v3, v6, v8
	v_pk_add_f32 v[0:1], v[2:3], v[10:11]
	v_mov_b32_e32 v12, v3
	v_mov_b32_e32 v13, v1
	v_mov_b32_e32 v7, v11
	v_pk_add_f32 v[6:7], v[12:13], v[6:7] neg_lo:[0,1] neg_hi:[0,1]
	v_mov_b32_e32 v9, v3
	v_pk_add_f32 v[6:7], v[8:9], v[6:7] neg_lo:[0,1] neg_hi:[0,1]
	v_mov_b32_e32 v11, v0
	v_add_f32_e32 v3, v14, v6
	v_add_f32_e32 v3, v3, v7
	v_pk_add_f32 v[6:7], v[0:1], v[2:3] neg_lo:[0,1] neg_hi:[0,1]
	v_pk_add_f32 v[8:9], v[0:1], v[2:3]
	v_mov_b32_e32 v2, v3
	v_mov_b32_e32 v7, v9
	v_pk_add_f32 v[12:13], v[10:11], v[6:7] neg_lo:[0,1] neg_hi:[0,1]
	v_pk_add_f32 v[6:7], v[10:11], v[6:7]
	v_mov_b32_e32 v3, v0
	v_pk_add_f32 v[10:11], v[6:7], v[0:1] op_sel:[1,0] op_sel_hi:[0,1] neg_lo:[0,1] neg_hi:[0,1]
	v_pk_add_f32 v[14:15], v[8:9], v[10:11] op_sel_hi:[1,0] neg_lo:[0,1] neg_hi:[0,1]
	v_mov_b32_e32 v8, v9
	v_mov_b32_e32 v9, v7
	v_pk_mov_b32 v[10:11], v[0:1], v[10:11] op_sel:[1,0]
	v_mov_b32_e32 v14, v12
	v_pk_add_f32 v[8:9], v[8:9], v[10:11] neg_lo:[0,1] neg_hi:[0,1]
	v_mov_b32_e32 v13, v7
	v_pk_add_f32 v[0:1], v[2:3], v[8:9] neg_lo:[0,1] neg_hi:[0,1]
	v_ashrrev_i32_e32 v5, 4, v4
	v_pk_add_f32 v[2:3], v[14:15], v[0:1]
	s_nop 0
	v_pk_add_f32 v[8:9], v[2:3], v[2:3] op_sel:[0,1] op_sel_hi:[1,0]
	s_nop 0
	v_pk_add_f32 v[6:7], v[6:7], v[8:9] op_sel:[1,0] op_sel_hi:[0,1]
	v_mov_b32_e32 v3, v6
	v_pk_add_f32 v[10:11], v[2:3], v[12:13] neg_lo:[0,1] neg_hi:[0,1]
	v_mov_b32_e32 v1, v8
	v_sub_f32_e32 v2, v2, v10
	v_pk_add_f32 v[0:1], v[0:1], v[10:11] neg_lo:[0,1] neg_hi:[0,1]
	v_sub_f32_e32 v2, v12, v2
	v_add_f32_e32 v0, v0, v2
	v_add_f32_e32 v0, v0, v1
	v_add_f32_e32 v1, v6, v0
	v_sub_f32_e32 v2, v1, v6
	v_sub_f32_e32 v0, v0, v2
	v_mul_f32_e32 v2, v16, v1
	v_fma_f32 v1, v16, v1, -v2
	v_fmac_f32_e32 v1, v16, v0
	v_add_f32_e32 v0, v2, v1
	v_cmp_class_f32_e64 s[0:1], v2, s4
	v_sub_f32_e32 v3, v0, v2
	v_sub_f32_e32 v1, v1, v3
	v_cndmask_b32_e64 v0, v0, v2, s[0:1]
	v_mov_b32_e32 v2, 0x37000000
	v_cmp_eq_f32_e64 s[0:1], s6, v0
	s_nop 1
	v_cndmask_b32_e64 v2, 0, v2, s[0:1]
	v_sub_f32_e32 v3, v0, v2
	s_mov_b32 s0, 0x3fb8aa3b
	v_mul_f32_e32 v6, 0x3fb8aa3b, v3
	v_fma_f32 v7, v3, s0, -v6
	v_rndne_f32_e32 v8, v6
	v_fmamk_f32 v7, v3, 0x32a5705f, v7
	v_sub_f32_e32 v6, v6, v8
	v_add_f32_e32 v6, v6, v7
	v_exp_f32_e32 v6, v6
	v_cvt_i32_f32_e32 v7, v8
	v_cmp_neq_f32_e64 s[0:1], |v0|, s5
	s_nop 1
	v_cndmask_b32_e64 v0, 0, v1, s[0:1]
	s_mov_b32 s0, 0xc2ce8ed0
	v_ldexp_f32 v1, v6, v7
	v_cmp_ngt_f32_e64 s[0:1], s0, v3
	v_add_f32_e32 v0, v2, v0
	v_mov_b32_e32 v2, 0x7f800000
	v_cndmask_b32_e64 v1, 0, v1, s[0:1]
	v_cmp_nlt_f32_e64 s[0:1], s6, v3
	s_nop 1
	v_cndmask_b32_e64 v1, v2, v1, s[0:1]
	v_fma_f32 v0, v1, v0, v1
	v_cmp_class_f32_e64 s[0:1], v1, s4
	s_nop 1
	v_cndmask_b32_e64 v0, v0, v1, s[0:1]
	v_cmp_neq_f32_e64 s[0:1], v16, |v16|
	s_nop 1
	v_cndmask_b32_e64 v1, v2, 0, s[0:1]
	v_cvt_f32_i32_e32 v2, v5
	v_cndmask_b32_e64 v1, v1, 1.0, vcc
	v_cmp_class_f32_e64 s[0:1], v16, s4
	s_nop 1
	v_cndmask_b32_e64 v0, |v0|, v1, s[0:1]
	v_mul_f32_e32 v0, v0, v2
	s_brev_b32 s0, 18
	v_and_b32_e32 v1, 0x7fffffff, v0
	v_cmp_nlt_f32_e64 s[0:1], |v0|, s0
	s_and_saveexec_b64 s[4:5], s[0:1]
	s_xor_b64 s[10:11], exec, s[4:5]
	s_cbranch_execz .LBB0_130
; __global__ void __launch_bounds__(NWAVES * 64, 2) mk_fwd(Args args) {
;     ...
;         if (gtid < 1024) { const int pos = gtid >> 4, i = gtid & 15; const float fr = powf(10000.f, -(float)i / 16.f); const float ang = (float)pos * fr; float sn, cs; sincosf(ang, &sn, &cs); tab[gtid] = (f32x2){cs, sn}; }
	v_lshrrev_b32_e32 v2, 23, v1
	v_add_u32_e32 v2, 0xffffff88, v2
	v_not_b32_e32 v3, 63
	v_cmp_lt_u32_e32 vcc, 63, v2
	s_mov_b32 s6, 0xfe5163ab
	v_mov_b32_e32 v7, 0
	v_cndmask_b32_e32 v3, 0, v3, vcc
	v_add_u32_e32 v2, v3, v2
	v_not_b32_e32 v3, 31
	v_cmp_lt_u32_e64 s[0:1], 31, v2
	s_nop 1
	v_cndmask_b32_e64 v5, 0, v3, s[0:1]
	v_add_u32_e32 v2, v5, v2
	v_cmp_lt_u32_e64 s[4:5], 31, v2
	s_nop 1
	v_cndmask_b32_e64 v3, 0, v3, s[4:5]
	v_add_u32_e32 v5, v3, v2
	v_and_b32_e32 v2, 0x7fffff, v1
	v_or_b32_e32 v18, 0x800000, v2
	v_mad_u64_u32 v[2:3], s[6:7], v18, s6, 0
	v_mov_b32_e32 v6, v3
	s_mov_b32 s6, 0x3c439041
	v_mad_u64_u32 v[8:9], s[6:7], v18, s6, v[6:7]
	v_mov_b32_e32 v6, v9
	s_mov_b32 s6, 0xdb629599
	v_mad_u64_u32 v[10:11], s[6:7], v18, s6, v[6:7]
	v_mov_b32_e32 v6, v11
	s_mov_b32 s6, 0xf534ddc0
	v_mad_u64_u32 v[12:13], s[6:7], v18, s6, v[6:7]
	v_mov_b32_e32 v6, v13
	s_mov_b32 s6, 0xfc2757d1
	v_mad_u64_u32 v[14:15], s[6:7], v18, s6, v[6:7]
	v_mov_b32_e32 v6, v15
	s_mov_b32 s6, 0x4e441529
	v_mad_u64_u32 v[16:17], s[6:7], v18, s6, v[6:7]
	v_mov_b32_e32 v6, v17
	s_mov_b32 s6, 0xa2f9836e
	v_mad_u64_u32 v[6:7], s[6:7], v18, s6, v[6:7]
	v_cndmask_b32_e32 v3, v16, v12, vcc
	v_cndmask_b32_e32 v6, v6, v14, vcc
	v_cndmask_b32_e32 v7, v7, v16, vcc
	v_cndmask_b32_e64 v9, v6, v3, s[0:1]
	v_cndmask_b32_e64 v6, v7, v6, s[0:1]
	v_cndmask_b32_e32 v7, v14, v10, vcc
	v_cndmask_b32_e64 v3, v3, v7, s[0:1]
	v_cndmask_b32_e64 v6, v6, v9, s[4:5]
	v_cndmask_b32_e64 v9, v9, v3, s[4:5]
	v_sub_u32_e32 v11, 32, v5
	v_alignbit_b32 v13, v6, v9, v11
	v_cmp_eq_u32_e64 s[6:7], 0, v5
	v_cndmask_b32_e32 v2, v10, v2, vcc
	s_nop 0
	v_cndmask_b32_e64 v5, v13, v6, s[6:7]
	v_cndmask_b32_e32 v6, v12, v8, vcc
	v_cndmask_b32_e64 v7, v7, v6, s[0:1]
	v_cndmask_b32_e64 v3, v3, v7, s[4:5]
	v_alignbit_b32 v8, v9, v3, v11
	v_cndmask_b32_e64 v8, v8, v9, s[6:7]
	v_bfe_u32 v13, v5, 29, 1
	v_cndmask_b32_e64 v2, v6, v2, s[0:1]
	v_alignbit_b32 v9, v5, v8, 30
	v_sub_u32_e32 v14, 0, v13
	v_cndmask_b32_e64 v2, v7, v2, s[4:5]
	v_xor_b32_e32 v9, v9, v14
	v_alignbit_b32 v6, v3, v2, v11
	v_cndmask_b32_e64 v3, v6, v3, s[6:7]
	v_ffbh_u32_e32 v7, v9
	v_alignbit_b32 v6, v8, v3, 30
	v_min_u32_e32 v7, 32, v7
	v_alignbit_b32 v2, v3, v2, 30
	v_xor_b32_e32 v6, v6, v14
	v_sub_u32_e32 v8, 31, v7
	v_xor_b32_e32 v2, v2, v14
	v_alignbit_b32 v9, v9, v6, v8
	v_alignbit_b32 v2, v6, v2, v8
	v_alignbit_b32 v3, v9, v2, 9
	v_ffbh_u32_e32 v6, v3
	v_min_u32_e32 v6, 32, v6
	v_lshrrev_b32_e32 v12, 29, v5
	v_not_b32_e32 v8, v6
	v_alignbit_b32 v2, v3, v2, v8
	v_lshlrev_b32_e32 v3, 31, v12
	v_or_b32_e32 v8, 0x33000000, v3
	v_add_lshl_u32 v6, v6, v7, 23
	v_lshrrev_b32_e32 v2, 9, v2
	v_sub_u32_e32 v6, v8, v6
	v_or_b32_e32 v3, 0.5, v3
	v_lshlrev_b32_e32 v7, 23, v7
	v_or_b32_e32 v2, v6, v2
	v_lshrrev_b32_e32 v6, 9, v9
	v_sub_u32_e32 v3, v3, v7
	v_or_b32_e32 v3, v6, v3
	s_mov_b32 s0, 0x3fc90fda
	v_mul_f32_e32 v6, 0x3fc90fda, v3
	v_fma_f32 v7, v3, s0, -v6
	v_fmamk_f32 v3, v3, 0x33a22168, v7
	v_fmac_f32_e32 v3, 0x3fc90fda, v2
	v_add_f32_e32 v2, v6, v3
	v_lshrrev_b32_e32 v3, 30, v5
	v_add_u32_e32 v3, v13, v3
